# mixers queue: original interleave, but the last 32 groups' retention-sample units moved to the very end (short-unit tail)
# speedup vs baseline: 1.0065x; 1.0012x over previous
; __device__ __forceinline__ void phase_mixers(const Params& p, LAS unsigned char* lds, int rep) {
;     ...
;     const int u = (int)__builtin_amdgcn_readfirstlane(*slot);
;     if (u >= 2304) break;
;     if (threadIdx.x == 0) nxt = atomicAdd(ctr, 1u);
;     if (u < 128) mix_ret_prompt(p, lds, u);
;     else {
;       const int v = u - 128, g = v / 17, s = v % 17;
;       if (s < 8) mix_ret_sample(p, lds, g * 8 + s);
;       else if (s < 12) mix_ma_sample(p, lds, g * 4 + (s - 8));
;       else if (s < 14) mix_ma_prompt(p, lds, g * 2 + (s - 12));
;       else if (s < 16) mix_sg_prompt(p, lds, g * 2 + (s - 14));
;       else mix_sg_sample(p, lds, g);
.LBB0_193:
	s_add_i32 s29, s42, 0xff80
	s_and_b32 s29, s29, 0xffff
	s_cmpk_lt_u32 s29, 0x660
	s_cbranch_scc1 .Lq_done
	s_cmpk_lt_u32 s29, 0x780
	s_cbranch_scc0 .Lq_late
	s_sub_i32 s29, s29, 0x660
	s_mul_i32 s34, s29, 0x1c72
	s_lshr_b32 s34, s34, 16
	s_mul_i32 s35, s34, 9
	s_sub_i32 s35, s29, s35
	s_mul_i32 s34, s34, 17
	s_add_i32 s29, s34, s35
	s_add_i32 s29, s29, 0x668
	s_branch .Lq_done
.Lq_late:
	s_sub_i32 s29, s29, 0x780
	s_lshr_b32 s34, s29, 3
	s_and_b32 s35, s29, 7
	s_mul_i32 s34, s34, 17
	s_add_i32 s29, s34, s35
	s_add_i32 s29, s29, 0x660
